# P6 item prologue: 4 halo loads issued together; weight/halo loads no longer waited before the first batch's row loads (counted vmcnt(32) at the first batch top)
# baseline (speedup 1.0000x reference)
; __device__ __forceinline__ float bf2f(unsigned b) { return __uint_as_float(b << 16); }
; __device__ __forceinline__ void act_item(int item, u16* UP, const u16* HALO, const float* sconv, const float* wconv, const float* bconv, float* out, int lane) {
;     const int rb = item / 22, cch = item - rb * 22, j0 = cch * 128 + 2 * lane;
;     float wgt[3][2], wvl[3][2], bg[2], bv[2];
; #pragma unroll
;     for (int k = 0; k < 3; ++k) { const f32x2 a = *(const f32x2*)(wconv + k * FF2 + j0), b = *(const f32x2*)(wconv + k * FF2 + FF + j0); wgt[k][0] = a.x; wgt[k][1] = a.y; wvl[k][0] = b.x; wvl[k][1] = b.y; }
;     { const f32x2 a = *(const f32x2*)(bconv + j0), b = *(const f32x2*)(bconv + FF + j0); bg[0] = a.x; bg[1] = a.y; bv[0] = b.x; bv[1] = b.y; }
;     const bool sample = rb >= 256;
;     float g2[2] = {0.f, 0.f}, g1[2] = {0.f, 0.f}, v2[2] = {0.f, 0.f}, v1[2] = {0.f, 0.f};
;     if (!sample && (rb & 31) != 0) {
;         const unsigned a = *(const unsigned*)(HALO + (size_t)((rb - 1) * 2) * FF2 + j0), b = *(const unsigned*)(HALO + (size_t)((rb - 1) * 2) * FF2 + FF + j0);
;         const unsigned c = *(const unsigned*)(HALO + (size_t)((rb - 1) * 2 + 1) * FF2 + j0), dd = *(const unsigned*)(HALO + (size_t)((rb - 1) * 2 + 1) * FF2 + FF + j0);
;         g2[0] = bf2f(a & 0xffffu); g2[1] = bf2f(a >> 16); v2[0] = bf2f(b & 0xffffu); v2[1] = bf2f(b >> 16);
;         g1[0] = bf2f(c & 0xffffu); g1[1] = bf2f(c >> 16); v1[0] = bf2f(dd & 0xffffu); v1[1] = bf2f(dd >> 16);
;     }
.LBB0_771:
	s_mul_hi_i32 s0, s80, 0x2e8ba2e9
	s_lshr_b32 s1, s0, 31
	s_ashr_i32 s0, s0, 2
	s_add_i32 s0, s0, s1
	s_mul_i32 s1, s0, 0xffffffea
	s_add_i32 s1, s1, s80
	v_lshl_or_b32 v2, s1, 7, v41
	v_ashrrev_i32_e32 v3, 31, v2
	v_lshlrev_b64 v[16:17], 2, v[2:3]
	v_lshl_add_u64 v[4:5], s[42:43], 0, v[16:17]
	v_lshl_add_u64 v[6:7], s[36:37], 0, v[16:17]
	v_lshl_add_u64 v[8:9], s[38:39], 0, v[16:17]
	v_lshl_add_u64 v[10:11], s[40:41], 0, v[16:17]
	global_load_dwordx2 v[4:5], v[4:5], off
	s_nop 0
	global_load_dwordx2 v[6:7], v[6:7], off
	s_nop 0
	global_load_dwordx2 v[8:9], v[8:9], off
	s_nop 0
	global_load_dwordx2 v[10:11], v[10:11], off
	v_lshl_add_u64 v[12:13], s[46:47], 0, v[16:17]
	v_lshl_add_u64 v[14:15], s[54:55], 0, v[16:17]
	v_lshl_add_u64 v[18:19], s[44:45], 0, v[16:17]
	global_load_dwordx2 v[12:13], v[12:13], off
	s_nop 0
	global_load_dwordx2 v[14:15], v[14:15], off
	v_lshl_add_u64 v[20:21], s[56:57], 0, v[16:17]
	global_load_dwordx2 v[16:17], v[18:19], off
	s_nop 0
	global_load_dwordx2 v[18:19], v[20:21], off
	s_cmpk_gt_i32 s80, 0x15ff
	s_cselect_b64 s[58:59], -1, 0
	s_cmpk_lt_i32 s80, 0x1600
	s_cselect_b64 s[60:61], -1, 0
	s_and_b32 s1, s0, 31
	s_cmp_eq_u32 s1, 0
	s_cselect_b64 s[6:7], -1, 0
	s_or_b64 s[6:7], s[58:59], s[6:7]
	v_mov_b32_e32 v1, v0
	s_and_b64 vcc, exec, s[6:7]
	v_mov_b64_e32 v[50:51], v[0:1]
	v_mov_b64_e32 v[48:49], v[0:1]
	v_mov_b64_e32 v[54:55], v[0:1]
	v_mov_b64_e32 v[52:53], v[0:1]
	s_mov_b32 s99, 0
	s_cbranch_vccnz .LBB0_773
	s_lshl_b32 s62, s0, 1
	s_mul_i32 s7, s0, 0x5800
	s_add_i32 s6, s62, -2
	s_addk_i32 s7, 0xa800
	s_mul_hi_i32 s63, s6, 0x2c00
	s_add_u32 s6, s18, s7
	s_addc_u32 s7, s19, s63
	v_lshlrev_b64 v[20:21], 1, v[2:3]
	v_lshl_add_u64 v[22:23], s[6:7], 0, v[20:21]
	s_add_i32 s6, s62, -1
	s_mul_hi_i32 s7, s6, 0x2c00
	s_mulk_i32 s6, 0x2c00
	s_add_u32 s6, s18, s6
	v_add_co_u32_e32 v24, vcc, 0x1000, v22
	s_addc_u32 s7, s19, s7
	s_nop 0
	v_addc_co_u32_e32 v25, vcc, 0, v23, vcc
	v_lshl_add_u64 v[20:21], s[6:7], 0, v[20:21]
	global_load_dword v124, v[22:23], off
	global_load_dword v125, v[24:25], off offset:1536
	global_load_dword v126, v[20:21], off
	v_add_co_u32_e32 v20, vcc, s71, v20
	s_nop 1
	v_addc_co_u32_e32 v21, vcc, 0, v21, vcc
	global_load_dword v127, v[20:21], off offset:1536
	s_mov_b32 s99, 1
.LBB0_773:
	s_ashr_i32 s6, s0, 5
	s_ashr_i32 s7, s6, 31
	s_lshl_b32 s81, s0, 6
	s_lshl_b64 s[62:63], s[6:7], 1
	s_mul_hi_i32 s7, s6, 0xb000
	s_mul_i32 s6, s6, 0xb000
	s_add_u32 s6, s3, s6
	s_addc_u32 s7, s21, s7
	v_lshl_add_u64 v[20:21], v[2:3], 2, s[6:7]
	s_mov_b64 s[6:7], 0x2c00
	v_lshl_add_u64 v[22:23], v[20:21], 0, s[6:7]
	s_lshl_b32 s82, s1, 6
	s_mul_i32 s1, s0, 0xb00
	s_mul_i32 s6, s0, 0xb0000
	v_subrev_u32_e32 v44, s1, v43
	s_mul_hi_i32 s1, s81, 0x2c00
	s_add_u32 s64, s92, s6
	s_addc_u32 s65, s93, s1
	v_ashrrev_i32_e32 v45, 31, v44
	s_mul_hi_i32 s0, s0, 0xb0000
	s_add_u32 s66, s92, s6
	v_lshlrev_b64 v[44:45], 1, v[44:45]
	s_addc_u32 s67, s93, s0
	s_mov_b32 s83, 0
	s_branch .LBB0_775

; __device__ __forceinline__ float bf2f(unsigned b) { return __uint_as_float(b << 16); }
; __device__ __forceinline__ void act_item(int item, u16* UP, const u16* HALO, const float* sconv, const float* wconv, const float* bconv, float* out, int lane) {
;     ...
;     if (!sample && (rb & 31) != 0) {
;         const unsigned a = *(const unsigned*)(HALO + (size_t)((rb - 1) * 2) * FF2 + j0), b = *(const unsigned*)(HALO + (size_t)((rb - 1) * 2) * FF2 + FF + j0);
;         const unsigned c = *(const unsigned*)(HALO + (size_t)((rb - 1) * 2 + 1) * FF2 + j0), dd = *(const unsigned*)(HALO + (size_t)((rb - 1) * 2 + 1) * FF2 + FF + j0);
;         g2[0] = bf2f(a & 0xffffu); g2[1] = bf2f(a >> 16); v2[0] = bf2f(b & 0xffffu); v2[1] = bf2f(b >> 16);
;         g1[0] = bf2f(c & 0xffffu); g1[1] = bf2f(c >> 16); v1[0] = bf2f(dd & 0xffffu); v1[1] = bf2f(dd >> 16);
;     }
;     for (int tb = 0; tb < 64; tb += 16) {
;         unsigned gw[16], vw[16];
; #pragma unroll
;         for (int t = 0; t < 16; ++t) { const size_t row = (size_t)rb * 64 + tb + t; gw[t] = *(const unsigned*)(UP + row * FF2 + j0); vw[t] = *(const unsigned*)(UP + row * FF2 + FF + j0); }
.LBB0_775:
	v_lshl_add_u64 v[60:61], s[66:67], 0, v[44:45]
	v_add_co_u32_e32 v46, vcc, 0x4300000, v60
	s_nop 1
	v_addc_co_u32_e32 v47, vcc, 0, v61, vcc
	v_add_co_u32_e32 v56, vcc, 0x4301000, v60
	s_nop 1
	v_addc_co_u32_e32 v57, vcc, 0, v61, vcc
	v_add_co_u32_e32 v58, vcc, 0x4302000, v60
	s_nop 1
	v_addc_co_u32_e32 v59, vcc, 0, v61, vcc
	v_add_co_u32_e32 v62, vcc, 0x4304000, v60
	s_nop 1
	v_addc_co_u32_e32 v63, vcc, 0, v61, vcc
	v_add_co_u32_e32 v64, vcc, 0x4305000, v60
	s_nop 1
	v_addc_co_u32_e32 v65, vcc, 0, v61, vcc
	v_add_co_u32_e32 v66, vcc, 0x4306000, v60
	s_nop 1
	v_addc_co_u32_e32 v67, vcc, 0, v61, vcc
	v_add_co_u32_e32 v68, vcc, 0x4308000, v60
	s_nop 1
	v_addc_co_u32_e32 v69, vcc, 0, v61, vcc
	v_add_co_u32_e32 v70, vcc, 0x4309000, v60
	s_nop 1
	v_addc_co_u32_e32 v71, vcc, 0, v61, vcc
	global_load_dword v47, v[46:47], off
	s_nop 0
	global_load_dword v46, v[56:57], off offset:1536
	s_nop 0
	global_load_dword v58, v[58:59], off offset:3072
	s_nop 0
	global_load_dword v59, v[62:63], off offset:512
	global_load_dword v56, v[64:65], off offset:2048
	global_load_dword v57, v[66:67], off offset:3584
	global_load_dword v87, v[68:69], off offset:1024
	global_load_dword v88, v[70:71], off offset:2560
	v_add_co_u32_e32 v62, vcc, 0x430b000, v60
	s_nop 1
	v_addc_co_u32_e32 v63, vcc, 0, v61, vcc
	v_add_co_u32_e32 v64, vcc, 0x430c000, v60
	s_nop 1
	v_addc_co_u32_e32 v65, vcc, 0, v61, vcc
	v_add_co_u32_e32 v66, vcc, 0x430d000, v60
	s_nop 1
	v_addc_co_u32_e32 v67, vcc, 0, v61, vcc
	v_add_co_u32_e32 v68, vcc, 0x430f000, v60
	s_nop 1
	v_addc_co_u32_e32 v69, vcc, 0, v61, vcc
	v_add_co_u32_e32 v70, vcc, 0x4310000, v60
	s_nop 1
	v_addc_co_u32_e32 v71, vcc, 0, v61, vcc
	v_add_co_u32_e32 v72, vcc, 0x4311000, v60
	s_nop 1
	v_addc_co_u32_e32 v73, vcc, 0, v61, vcc
	v_add_co_u32_e32 v74, vcc, 0x4313000, v60
	s_nop 1
	v_addc_co_u32_e32 v75, vcc, 0, v61, vcc
	v_add_co_u32_e32 v76, vcc, 0x4314000, v60
	s_nop 1
	v_addc_co_u32_e32 v77, vcc, 0, v61, vcc
	global_load_dword v86, v[62:63], off
	global_load_dword v85, v[64:65], off offset:1536
	global_load_dword v83, v[66:67], off offset:3072
	global_load_dword v84, v[68:69], off offset:512
	global_load_dword v81, v[70:71], off offset:2048
	global_load_dword v82, v[72:73], off offset:3584
	global_load_dword v79, v[74:75], off offset:1024
	global_load_dword v80, v[76:77], off offset:2560
	v_add_co_u32_e32 v62, vcc, 0x4316000, v60
	s_nop 1
	v_addc_co_u32_e32 v63, vcc, 0, v61, vcc
	v_add_co_u32_e32 v64, vcc, 0x4317000, v60
	s_nop 1
	v_addc_co_u32_e32 v65, vcc, 0, v61, vcc
	v_add_co_u32_e32 v66, vcc, 0x4318000, v60
	s_nop 1
	v_addc_co_u32_e32 v67, vcc, 0, v61, vcc
	v_add_co_u32_e32 v68, vcc, 0x431a000, v60
	s_nop 1
	v_addc_co_u32_e32 v69, vcc, 0, v61, vcc
	v_add_co_u32_e32 v70, vcc, 0x431b000, v60
	s_nop 1
	v_addc_co_u32_e32 v71, vcc, 0, v61, vcc
	v_add_co_u32_e32 v90, vcc, 0x431c000, v60
	s_nop 1
	v_addc_co_u32_e32 v91, vcc, 0, v61, vcc
	v_add_co_u32_e32 v92, vcc, 0x431e000, v60
	s_nop 1
	v_addc_co_u32_e32 v93, vcc, 0, v61, vcc
	v_add_co_u32_e32 v94, vcc, 0x431f000, v60
	s_nop 1
	v_addc_co_u32_e32 v95, vcc, 0, v61, vcc
	global_load_dword v78, v[62:63], off
	global_load_dword v77, v[64:65], off offset:1536
	global_load_dword v75, v[66:67], off offset:3072
	global_load_dword v76, v[68:69], off offset:512
	global_load_dword v73, v[70:71], off offset:2048
	global_load_dword v74, v[90:91], off offset:3584
	s_nop 0
	global_load_dword v71, v[92:93], off offset:1024
	global_load_dword v72, v[94:95], off offset:2560
	v_add_co_u32_e32 v62, vcc, 0x4321000, v60
	s_nop 1
	v_addc_co_u32_e32 v63, vcc, 0, v61, vcc
	v_add_co_u32_e32 v64, vcc, 0x4322000, v60
	s_nop 1
	v_addc_co_u32_e32 v65, vcc, 0, v61, vcc
	v_add_co_u32_e32 v66, vcc, 0x4323000, v60
	s_nop 1
	v_addc_co_u32_e32 v67, vcc, 0, v61, vcc
	v_add_co_u32_e32 v90, vcc, 0x4325000, v60
	s_nop 1
	v_addc_co_u32_e32 v91, vcc, 0, v61, vcc
	v_add_co_u32_e32 v92, vcc, 0x4326000, v60
	s_nop 1
	v_addc_co_u32_e32 v93, vcc, 0, v61, vcc
	v_add_co_u32_e32 v94, vcc, 0x4327000, v60
	s_nop 1
	v_addc_co_u32_e32 v95, vcc, 0, v61, vcc
	v_add_co_u32_e32 v96, vcc, 0x4329000, v60
	s_nop 1
	v_addc_co_u32_e32 v97, vcc, 0, v61, vcc
	v_add_co_u32_e32 v60, vcc, 0x432a000, v60
	s_nop 1
	v_addc_co_u32_e32 v61, vcc, 0, v61, vcc
	global_load_dword v70, v[62:63], off
	global_load_dword v69, v[64:65], off offset:1536
	s_nop 0
	global_load_dword v66, v[66:67], off offset:3072
	s_nop 0
	global_load_dword v67, v[90:91], off offset:512
	global_load_dword v64, v[92:93], off offset:2048
	global_load_dword v65, v[94:95], off offset:3584
	global_load_dword v1, v[96:97], off offset:1024
	global_load_dword v68, v[60:61], off offset:2560
	s_cmp_lg_u32 s83, 0
	s_cbranch_scc1 .Lp6_nf
	s_waitcnt vmcnt(32)
	s_cmp_eq_u32 s99, 0
	s_cbranch_scc1 .Lp6_nh
	v_lshlrev_b32_e32 v48, 16, v124
	v_and_b32_e32 v49, 0xffff0000, v124
	v_lshlrev_b32_e32 v50, 16, v125
	v_and_b32_e32 v51, 0xffff0000, v125
	v_lshlrev_b32_e32 v52, 16, v126
	v_and_b32_e32 v53, 0xffff0000, v126
	v_lshlrev_b32_e32 v54, 16, v127
	v_and_b32_e32 v55, 0xffff0000, v127
; __device__ __forceinline__ void act_item(int item, u16* UP, const u16* HALO, const float* sconv, const float* wconv, const float* bconv, float* out, int lane) {
;     ...
;     for (int k = 0; k < 3; ++k) { const f32x2 a = *(const f32x2*)(wconv + k * FF2 + j0), b = *(const f32x2*)(wconv + k * FF2 + FF + j0); wgt[k][0] = a.x; wgt[k][1] = a.y; wvl[k][0] = b.x; wvl[k][1] = b.y; }
;     { const f32x2 a = *(const f32x2*)(bconv + j0), b = *(const f32x2*)(bconv + FF + j0); bg[0] = a.x; bg[1] = a.y; bv[0] = b.x; bv[1] = b.y; }
;     ...
;             if (sample && (t & 3) == 0) { const int ns = (row - TP) >> 2; const float* s0 = sconv + (size_t)ns * 2 * FF2;
;                 const f32x2 a = *(const f32x2*)(s0 + j0), b = *(const f32x2*)(s0 + FF + j0), c = *(const f32x2*)(s0 + FF2 + j0), dd = *(const f32x2*)(s0 + FF2 + FF + j0);
;                 g2[0] = a.x; g2[1] = a.y; v2[0] = b.x; v2[1] = b.y; g1[0] = c.x; g1[1] = c.y; v1[0] = dd.x; v1[1] = dd.y; }
.Lp6_nh:
	v_mov_b32_e32 v24, v18
	v_mov_b32_e32 v25, v16
	v_mov_b32_e32 v26, v6
	v_mov_b32_e32 v27, v4
	v_mov_b32_e32 v28, v10
	v_mov_b32_e32 v29, v8
	v_mov_b32_e32 v30, v14
	v_mov_b32_e32 v31, v12
	v_mov_b32_e32 v32, v19
	v_mov_b32_e32 v33, v17
	v_mov_b32_e32 v34, v7
	v_mov_b32_e32 v35, v5
	v_mov_b32_e32 v36, v11
	v_mov_b32_e32 v37, v9
	v_mov_b32_e32 v38, v15
	v_mov_b32_e32 v39, v13
	v_mov_b32_e32 v40, v15
	v_mov_b32_e32 v42, v11
.Lp6_nf:
	v_cndmask_b32_e64 v60, 0, 1, s[58:59]
	v_cmp_ne_u32_e64 s[6:7], 1, v60
	s_andn2_b64 vcc, exec, s[58:59]
	s_cbranch_vccnz .LBB0_777
	s_add_i32 s0, s81, s83
	s_addk_i32 s0, 0xc000
	s_ashr_i32 s0, s0, 2
	s_mul_hi_i32 s1, s0, 0xb000
	s_mul_i32 s0, s0, 0xb000
	s_add_u32 s0, s22, s0
	s_addc_u32 s1, s23, s1
	v_lshl_add_u64 v[48:49], v[2:3], 2, s[0:1]
	v_add_co_u32_e32 v50, vcc, 0x2000, v48
	s_nop 1
	v_addc_co_u32_e32 v51, vcc, 0, v49, vcc
	v_add_co_u32_e32 v52, vcc, 0x5000, v48
	s_nop 1
	v_addc_co_u32_e32 v53, vcc, 0, v49, vcc
	v_add_co_u32_e32 v54, vcc, 0x8000, v48
	s_nop 1
	v_addc_co_u32_e32 v55, vcc, 0, v49, vcc
	s_add_u32 s68, s0, 0xb000
	s_addc_u32 s69, s1, 0
	v_lshl_add_u64 v[100:101], v[2:3], 2, s[68:69]
	global_load_dwordx2 v[100:101], v[100:101], off
	s_add_u32 s68, s0, 0xdc00
	s_addc_u32 s69, s1, 0
	v_lshl_add_u64 v[102:103], v[2:3], 2, s[68:69]
	global_load_dwordx2 v[102:103], v[102:103], off
	s_add_u32 s68, s0, 0x10800
	s_addc_u32 s69, s1, 0
	v_lshl_add_u64 v[104:105], v[2:3], 2, s[68:69]
	global_load_dwordx2 v[104:105], v[104:105], off
	s_add_u32 s68, s0, 0x13400
	s_addc_u32 s69, s1, 0
	v_lshl_add_u64 v[106:107], v[2:3], 2, s[68:69]
	global_load_dwordx2 v[106:107], v[106:107], off
	s_add_u32 s68, s0, 0x16000
	s_addc_u32 s69, s1, 0
	v_lshl_add_u64 v[108:109], v[2:3], 2, s[68:69]
	global_load_dwordx2 v[108:109], v[108:109], off
	s_add_u32 s68, s0, 0x18c00
	s_addc_u32 s69, s1, 0
	v_lshl_add_u64 v[110:111], v[2:3], 2, s[68:69]
	global_load_dwordx2 v[110:111], v[110:111], off
	s_add_u32 s68, s0, 0x1b800
	s_addc_u32 s69, s1, 0
	v_lshl_add_u64 v[112:113], v[2:3], 2, s[68:69]
	global_load_dwordx2 v[112:113], v[112:113], off
	s_add_u32 s68, s0, 0x1e400
	s_addc_u32 s69, s1, 0
	v_lshl_add_u64 v[114:115], v[2:3], 2, s[68:69]
	global_load_dwordx2 v[114:115], v[114:115], off
	s_add_u32 s68, s0, 0x21000
	s_addc_u32 s69, s1, 0
	v_lshl_add_u64 v[116:117], v[2:3], 2, s[68:69]
	global_load_dwordx2 v[116:117], v[116:117], off
	s_add_u32 s68, s0, 0x23c00
	s_addc_u32 s69, s1, 0
	v_lshl_add_u64 v[118:119], v[2:3], 2, s[68:69]
	global_load_dwordx2 v[118:119], v[118:119], off
	s_add_u32 s68, s0, 0x26800
	s_addc_u32 s69, s1, 0
	v_lshl_add_u64 v[120:121], v[2:3], 2, s[68:69]
	global_load_dwordx2 v[120:121], v[120:121], off
	s_add_u32 s68, s0, 0x29400
	s_addc_u32 s69, s1, 0
	v_lshl_add_u64 v[122:123], v[2:3], 2, s[68:69]
	global_load_dwordx2 v[122:123], v[122:123], off
	global_load_dwordx2 v[48:49], v[48:49], off
	s_nop 0
	global_load_dwordx2 v[50:51], v[50:51], off offset:3072
	s_nop 0
	global_load_dwordx2 v[52:53], v[52:53], off offset:2048
	s_nop 0
	global_load_dwordx2 v[54:55], v[54:55], off offset:1024
